# P15: final f32 output stores write-through (less dirty L2 to flush at kernel end)
# baseline (speedup 1.0000x reference)
.LBB0_1546:
	s_or_b64 exec, exec, s[0:1]
	s_lshl_b32 s19, s33, 3
	s_lshl_b32 s0, s33, 4
	s_andn2_b32 s0, s0, 63
	s_and_b32 s1, s19, 16
	v_lshl_or_b32 v36, s38, 5, v163
	s_or_b32 s9, s1, s0
	s_movk_i32 s0, 0x410
	v_mul_lo_u32 v36, v36, s0
	s_lshl_b32 s0, s39, 7
	v_lshlrev_b32_e32 v37, 1, v162
	s_and_b32 s8, s19, 8
	v_and_b32_e32 v37, 0xffffffe0, v37
	s_add_i32 s0, s0, 0
	s_add_i32 s12, s16, s9
	v_add3_u32 v136, s0, v36, v37
	s_or_b32 s0, s12, s8
	s_ashr_i32 s1, s0, 31
	s_lshl_b64 s[0:1], s[0:1], 4
	s_add_u32 s0, s4, s0
	s_barrier
	ds_write_b128 v136, v[128:131]
	ds_write_b128 v136, v[124:127] offset:16
	ds_write_b128 v136, v[120:123] offset:512
	ds_write_b128 v136, v[112:115] offset:528
	ds_write_b128 v136, v[116:119] offset:16640
	ds_write_b128 v136, v[108:111] offset:16656
	ds_write_b128 v136, v[104:107] offset:17152
	ds_write_b128 v136, v[132:135] offset:17168
	s_addc_u32 s1, s5, s1
	v_mov_b32_e32 v113, 0
	s_waitcnt lgkmcnt(0)
	s_barrier
	global_load_dwordx4 v[116:119], v113, s[0:1]
	global_load_dwordx4 v[120:123], v113, s[0:1] offset:16
	global_load_dwordx4 v[124:127], v113, s[0:1] offset:48
	global_load_dwordx4 v[128:131], v113, s[0:1] offset:32
	s_mov_b32 s0, 0x358637bd
	s_or_b32 s13, s8, 4
	v_mov_b64_e32 v[110:111], s[0:1]
	s_or_b32 s0, s12, s13
	s_ashr_i32 s1, s0, 31
	s_lshl_b64 s[0:1], s[0:1], 4
	v_lshl_add_u32 v112, v162, 4, 0
	s_mulk_i32 s33, 0x2080
	s_add_u32 s0, s4, s0
	v_add_u32_e32 v114, s33, v112
	s_addc_u32 s1, s5, s1
	ds_read_b128 v[132:135], v114
	global_load_dwordx4 v[36:39], v113, s[0:1] offset:48
	global_load_dwordx4 v[104:107], v113, s[0:1] offset:32
	global_load_dwordx4 v[138:141], v113, s[0:1] offset:16
	global_load_dwordx4 v[142:145], v113, s[0:1]
	s_or_b32 s12, s16, s8
	s_add_i32 s0, s12, s9
	s_ashr_i32 s1, s0, 31
	s_lshl_b64 s[0:1], s[0:1], 12
	s_add_u32 s0, s10, s0
	s_addc_u32 s1, s11, s1
	s_mov_b32 s6, 0x3a800000
	s_mov_b32 s7, 0x800000
	s_add_u32 s0, s0, s2
	v_lshlrev_b64 v[108:109], 2, v[156:157]
	s_addc_u32 s1, s1, s3
	v_lshl_add_u64 v[146:147], s[0:1], 0, v[108:109]
	s_or_b32 s14, s19, 1
	s_and_b32 s15, s14, 9
	s_mulk_i32 s14, 0x410
	v_add_u32_e32 v112, s14, v112
	s_waitcnt vmcnt(7)
	v_mov_b32_e32 v148, v117
	v_mov_b32_e32 v149, v118
	v_mov_b32_e32 v117, v119
	s_waitcnt vmcnt(6)
	v_mov_b32_e32 v118, v121
	v_mov_b32_e32 v119, v122
	v_mov_b32_e32 v121, v123
	v_pk_add_f32 v[116:117], v[148:149], v[116:117]
	v_pk_add_f32 v[118:119], v[118:119], v[120:121]
	v_mov_b32_e32 v121, v116
	v_mov_b32_e32 v120, v118
	v_mov_b32_e32 v116, v119
	v_pk_add_f32 v[116:117], v[120:121], v[116:117]
	s_nop 0
	v_pk_fma_f32 v[116:117], v[116:117], s[6:7], v[110:111] op_sel_hi:[1,0,0]
	s_nop 0
	v_mul_f32_e32 v118, 0x4b800000, v116
	v_cmp_gt_f32_e64 s[0:1], s7, v116
	v_mul_f32_e32 v115, 0x4b800000, v117
	v_cmp_gt_f32_e32 vcc, s7, v117
	v_cndmask_b32_e64 v116, v116, v118, s[0:1]
	v_rsq_f32_e32 v137, v116
	v_cndmask_b32_e32 v115, v117, v115, vcc
	v_rsq_f32_e32 v115, v115
	ds_read_b128 v[116:119], v112
	ds_read_b128 v[120:123], v112 offset:1040
	v_mul_f32_e32 v149, 0x45800000, v137
	v_cndmask_b32_e64 v150, v137, v149, s[0:1]
	s_or_b32 s0, s16, s15
	s_add_i32 s14, s0, s9
	s_ashr_i32 s15, s14, 31
	s_lshl_b64 s[14:15], s[14:15], 12
	v_mul_f32_e32 v148, 0x45800000, v115
	s_add_u32 s1, s10, s14
	v_cndmask_b32_e32 v148, v115, v148, vcc
	s_addc_u32 s15, s11, s15
	s_waitcnt lgkmcnt(2)
	v_pk_mul_f32 v[132:133], v[132:133], v[148:149] op_sel_hi:[1,0]
	v_pk_mul_f32 v[134:135], v[134:135], v[148:149] op_sel_hi:[1,0]
	s_add_u32 s14, s1, s2
	s_waitcnt lgkmcnt(1)
	v_pk_mul_f32 v[148:149], v[116:117], v[150:151] op_sel_hi:[1,0]
	v_pk_mul_f32 v[150:151], v[118:119], v[150:151] op_sel_hi:[1,0]
	v_pk_mul_f32 v[118:119], v[2:3], v[134:135]
	v_pk_mul_f32 v[116:117], v[0:1], v[132:133]
	s_addc_u32 s15, s15, s3
	global_store_dwordx4 v[146:147], v[116:119], off sc1
	v_lshl_add_u64 v[132:133], s[14:15], 0, v[108:109]
	s_or_b32 s1, s19, 2
	v_pk_mul_f32 v[118:119], v[2:3], v[150:151]
	v_pk_mul_f32 v[116:117], v[0:1], v[148:149]
	global_store_dwordx4 v[132:133], v[116:119], off sc1
	s_and_b32 s1, s1, 10
	s_or_b32 s1, s16, s1
	s_waitcnt vmcnt(6)
	v_mov_b32_e32 v116, v129
	v_mov_b32_e32 v117, v130
	v_mov_b32_e32 v129, v131
	v_mov_b32_e32 v118, v125
	v_mov_b32_e32 v119, v126
	v_mov_b32_e32 v125, v127
	v_pk_add_f32 v[116:117], v[116:117], v[128:129]
	v_pk_add_f32 v[118:119], v[118:119], v[124:125]
	v_mov_b32_e32 v125, v116
	v_mov_b32_e32 v124, v118
	v_mov_b32_e32 v116, v119
	v_pk_add_f32 v[116:117], v[124:125], v[116:117]
	s_add_i32 s14, s1, s9
	v_pk_fma_f32 v[124:125], v[116:117], s[6:7], v[110:111] op_sel_hi:[1,0,0]
	s_ashr_i32 s15, s14, 31
	v_mul_f32_e32 v115, 0x4b800000, v125
	v_cmp_gt_f32_e32 vcc, s7, v125
	s_lshl_b64 s[14:15], s[14:15], 12
	s_add_u32 s14, s10, s14
	v_cndmask_b32_e32 v115, v125, v115, vcc
	v_rsq_f32_e32 v115, v115
	s_addc_u32 s15, s11, s15
	s_add_u32 s14, s14, s2
	s_addc_u32 s15, s15, s3
	v_lshl_add_u64 v[128:129], s[14:15], 0, v[108:109]
	s_or_b32 s14, s19, 3
	v_mul_f32_e32 v125, 0x45800000, v115
	s_and_b32 s14, s14, 11
	v_cndmask_b32_e32 v126, v115, v125, vcc
	v_mul_f32_e32 v115, 0x4b800000, v124
	v_cmp_gt_f32_e32 vcc, s7, v124
	s_or_b32 s14, s16, s14
	s_add_i32 s20, s14, s9
	v_cndmask_b32_e32 v115, v124, v115, vcc
	v_rsq_f32_e32 v115, v115
	ds_read_b128 v[116:119], v112 offset:2080
	s_ashr_i32 s21, s20, 31
	s_waitcnt lgkmcnt(1)
	v_pk_mul_f32 v[120:121], v[120:121], v[126:127] op_sel_hi:[1,0]
	v_pk_mul_f32 v[122:123], v[122:123], v[126:127] op_sel_hi:[1,0]
	s_lshl_b64 s[20:21], s[20:21], 12
	v_pk_mul_f32 v[122:123], v[2:3], v[122:123]
	v_pk_mul_f32 v[120:121], v[0:1], v[120:121]
	s_add_u32 s15, s10, s20
	global_store_dwordx4 v[128:129], v[120:123], off sc1
	s_addc_u32 s17, s11, s21
	s_add_u32 s20, s15, s2
	v_mul_f32_e32 v120, 0x45800000, v115
	v_cndmask_b32_e32 v124, v115, v120, vcc
	ds_read_b128 v[120:123], v112 offset:3120
	s_waitcnt lgkmcnt(1)
	v_pk_mul_f32 v[116:117], v[116:117], v[124:125] op_sel_hi:[1,0]
	v_pk_mul_f32 v[118:119], v[118:119], v[124:125] op_sel_hi:[1,0]
	s_addc_u32 s21, s17, s3
	v_pk_mul_f32 v[118:119], v[2:3], v[118:119]
	v_pk_mul_f32 v[116:117], v[0:1], v[116:117]
	v_lshl_add_u64 v[124:125], s[20:21], 0, v[108:109]
	global_store_dwordx4 v[124:125], v[116:119], off sc1
	s_or_b32 s15, s19, 4
	s_and_b32 s15, s15, 12
	s_waitcnt vmcnt(4)
	v_mov_b32_e32 v116, v143
	v_mov_b32_e32 v117, v144
	v_mov_b32_e32 v143, v145
	v_mov_b32_e32 v118, v139
	v_mov_b32_e32 v119, v140
	v_mov_b32_e32 v139, v141
	v_pk_add_f32 v[116:117], v[116:117], v[142:143]
	v_pk_add_f32 v[118:119], v[118:119], v[138:139]
	v_mov_b32_e32 v127, v116
	v_mov_b32_e32 v126, v118
	v_mov_b32_e32 v116, v119
	v_pk_add_f32 v[116:117], v[126:127], v[116:117]
	s_or_b32 s15, s16, s15
	v_pk_fma_f32 v[126:127], v[116:117], s[6:7], v[110:111] op_sel_hi:[1,0,0]
	s_add_i32 s20, s15, s9
	v_mul_f32_e32 v115, 0x4b800000, v127
	v_cmp_gt_f32_e32 vcc, s7, v127
	s_ashr_i32 s21, s20, 31
	s_lshl_b64 s[20:21], s[20:21], 12
	v_cndmask_b32_e32 v115, v127, v115, vcc
	v_rsq_f32_e32 v115, v115
	s_add_u32 s17, s10, s20
	s_addc_u32 s18, s11, s21
	s_add_u32 s20, s17, s2
	s_addc_u32 s21, s18, s3
	s_or_b32 s17, s19, 5
	v_mul_f32_e32 v127, 0x45800000, v115
	s_and_b32 s17, s17, 13
	v_cndmask_b32_e32 v128, v115, v127, vcc
	v_mul_f32_e32 v115, 0x4b800000, v126
	v_cmp_gt_f32_e32 vcc, s7, v126
	s_or_b32 s17, s16, s17
	v_lshl_add_u64 v[124:125], s[20:21], 0, v[108:109]
	v_cndmask_b32_e32 v115, v126, v115, vcc
	v_rsq_f32_e32 v115, v115
	s_add_i32 s20, s17, s9
	ds_read_b128 v[116:119], v112 offset:4160
	s_ashr_i32 s21, s20, 31
	s_waitcnt lgkmcnt(1)
	v_pk_mul_f32 v[120:121], v[128:129], v[120:121] op_sel_hi:[0,1]
	v_pk_mul_f32 v[122:123], v[128:129], v[122:123] op_sel_hi:[0,1]
	s_lshl_b64 s[20:21], s[20:21], 12
	v_pk_mul_f32 v[122:123], v[2:3], v[122:123]
	v_pk_mul_f32 v[120:121], v[0:1], v[120:121]
	s_add_u32 s18, s10, s20
	global_store_dwordx4 v[124:125], v[120:123], off sc1
	s_addc_u32 s21, s11, s21
	s_add_u32 s20, s18, s2
	v_mul_f32_e32 v120, 0x45800000, v115
	v_cndmask_b32_e32 v124, v115, v120, vcc
	ds_read_b128 v[120:123], v112 offset:5200
	s_waitcnt lgkmcnt(1)
	v_pk_mul_f32 v[116:117], v[124:125], v[116:117] op_sel_hi:[0,1]
	v_pk_mul_f32 v[118:119], v[124:125], v[118:119] op_sel_hi:[0,1]
	s_addc_u32 s21, s21, s3
	v_pk_mul_f32 v[118:119], v[2:3], v[118:119]
	v_pk_mul_f32 v[116:117], v[0:1], v[116:117]
	v_lshl_add_u64 v[124:125], s[20:21], 0, v[108:109]
	global_store_dwordx4 v[124:125], v[116:119], off sc1
	s_or_b32 s18, s19, 6
	s_and_b32 s18, s18, 14
	v_mov_b32_e32 v116, v105
	v_mov_b32_e32 v117, v106
	v_mov_b32_e32 v105, v107
	v_mov_b32_e32 v106, v37
	v_mov_b32_e32 v107, v38
	v_mov_b32_e32 v37, v39
	v_pk_add_f32 v[104:105], v[116:117], v[104:105]
	v_pk_add_f32 v[36:37], v[106:107], v[36:37]
	v_mov_b32_e32 v39, v104
	v_mov_b32_e32 v38, v36
	v_mov_b32_e32 v104, v37
	s_or_b32 s18, s16, s18
	v_pk_add_f32 v[36:37], v[38:39], v[104:105]
	s_add_i32 s20, s18, s9
	v_pk_fma_f32 v[104:105], v[36:37], s[6:7], v[110:111] op_sel_hi:[1,0,0]
	s_ashr_i32 s21, s20, 31
	v_mul_f32_e32 v36, 0x4b800000, v105
	v_cmp_gt_f32_e32 vcc, s7, v105
	s_lshl_b64 s[20:21], s[20:21], 12
	s_add_u32 s20, s10, s20
	v_cndmask_b32_e32 v36, v105, v36, vcc
	v_rsq_f32_e32 v105, v36
	s_addc_u32 s21, s11, s21
	s_add_u32 s20, s20, s2
	s_addc_u32 s21, s21, s3
	s_or_b32 s19, s19, 7
	s_and_b32 s19, s19, 15
	v_mul_f32_e32 v106, 0x45800000, v105
	v_cndmask_b32_e32 v106, v105, v106, vcc
	v_mul_f32_e32 v105, 0x4b800000, v104
	v_cmp_gt_f32_e32 vcc, s7, v104
	s_or_b32 s19, s16, s19
	v_lshl_add_u64 v[116:117], s[20:21], 0, v[108:109]
	v_cndmask_b32_e32 v104, v104, v105, vcc
	s_add_i32 s20, s19, s9
	v_rsq_f32_e32 v115, v104
	s_ashr_i32 s21, s20, 31
	ds_read_b128 v[36:39], v112 offset:6240
	s_lshl_b64 s[20:21], s[20:21], 12
	s_waitcnt lgkmcnt(1)
	v_pk_mul_f32 v[118:119], v[106:107], v[120:121] op_sel_hi:[0,1]
	v_pk_mul_f32 v[106:107], v[106:107], v[122:123] op_sel_hi:[0,1]
	s_add_u32 s20, s10, s20
	v_pk_mul_f32 v[106:107], v[2:3], v[106:107]
	v_pk_mul_f32 v[104:105], v[0:1], v[118:119]
	s_addc_u32 s21, s11, s21
	global_store_dwordx4 v[116:117], v[104:107], off sc1
	s_add_u32 s20, s20, s2
	s_addc_u32 s21, s21, s3
	v_mul_f32_e32 v104, 0x45800000, v115
	v_cndmask_b32_e32 v104, v115, v104, vcc
	s_waitcnt lgkmcnt(0)
	v_pk_mul_f32 v[36:37], v[104:105], v[36:37] op_sel_hi:[0,1]
	v_pk_mul_f32 v[38:39], v[104:105], v[38:39] op_sel_hi:[0,1]
	v_lshl_add_u64 v[104:105], s[20:21], 0, v[108:109]
	s_or_b32 s20, s9, 32
	s_add_i32 s21, s16, s20
	s_or_b32 s22, s21, s8
	s_ashr_i32 s23, s22, 31
	s_lshl_b64 s[22:23], s[22:23], 4
	s_add_u32 s22, s4, s22
	v_pk_mul_f32 v[38:39], v[2:3], v[38:39]
	v_pk_mul_f32 v[36:37], v[0:1], v[36:37]
	s_addc_u32 s23, s5, s23
	global_store_dwordx4 v[104:105], v[36:39], off sc1
	s_barrier
	ds_write_b128 v136, v[96:99]
	ds_write_b128 v136, v[92:95] offset:16
	ds_write_b128 v136, v[88:91] offset:512
	ds_write_b128 v136, v[80:83] offset:528
	ds_write_b128 v136, v[84:87] offset:16640
	ds_write_b128 v136, v[76:79] offset:16656
	ds_write_b128 v136, v[72:75] offset:17152
	ds_write_b128 v136, v[100:103] offset:17168
	s_waitcnt lgkmcnt(0)
	s_barrier
	global_load_dwordx4 v[76:79], v113, s[22:23]
	global_load_dwordx4 v[80:83], v113, s[22:23] offset:16
	global_load_dwordx4 v[84:87], v113, s[22:23] offset:32
	global_load_dwordx4 v[88:91], v113, s[22:23] offset:48
	s_or_b32 s22, s21, s13
	s_ashr_i32 s23, s22, 31
	s_lshl_b64 s[22:23], s[22:23], 4
	s_add_u32 s22, s4, s22
	s_addc_u32 s23, s5, s23
	global_load_dwordx4 v[36:39], v113, s[22:23] offset:48
	global_load_dwordx4 v[72:75], v113, s[22:23] offset:32
	global_load_dwordx4 v[92:95], v113, s[22:23] offset:16
	global_load_dwordx4 v[96:99], v113, s[22:23]
	s_add_i32 s22, s12, s20
	s_ashr_i32 s23, s22, 31
	ds_read_b128 v[100:103], v114
	s_lshl_b64 s[22:23], s[22:23], 12
	s_add_u32 s21, s10, s22
	s_addc_u32 s23, s11, s23
	s_add_u32 s22, s21, s2
	s_addc_u32 s23, s23, s3
	s_waitcnt vmcnt(7)
	v_mov_b32_e32 v104, v77
	v_mov_b32_e32 v105, v78
	v_mov_b32_e32 v77, v79
	s_waitcnt vmcnt(6)
	v_mov_b32_e32 v78, v81
	v_mov_b32_e32 v79, v82
	v_mov_b32_e32 v81, v83
	v_pk_add_f32 v[76:77], v[104:105], v[76:77]
	v_pk_add_f32 v[78:79], v[78:79], v[80:81]
	v_mov_b32_e32 v81, v76
	v_mov_b32_e32 v80, v78
	v_mov_b32_e32 v76, v79
	v_pk_add_f32 v[76:77], v[80:81], v[76:77]
	v_lshl_add_u64 v[104:105], s[22:23], 0, v[108:109]
	v_pk_fma_f32 v[80:81], v[76:77], s[6:7], v[110:111] op_sel_hi:[1,0,0]
	s_add_i32 s22, s0, s20
	v_mul_f32_e32 v76, 0x4b800000, v81
	v_cmp_gt_f32_e32 vcc, s7, v81
	s_ashr_i32 s23, s22, 31
	s_lshl_b64 s[22:23], s[22:23], 12
	v_cndmask_b32_e32 v76, v81, v76, vcc
	v_rsq_f32_e32 v81, v76
	ds_read_b128 v[76:79], v112
	s_add_u32 s21, s10, s22
	s_addc_u32 s23, s11, s23
	v_mul_f32_e32 v82, 0x45800000, v81
	v_cndmask_b32_e32 v82, v81, v82, vcc
	v_mul_f32_e32 v81, 0x4b800000, v80
	v_cmp_gt_f32_e32 vcc, s7, v80
	s_waitcnt lgkmcnt(1)
	v_pk_mul_f32 v[100:101], v[100:101], v[82:83] op_sel_hi:[1,0]
	v_pk_mul_f32 v[82:83], v[102:103], v[82:83] op_sel_hi:[1,0]
	v_cndmask_b32_e32 v80, v80, v81, vcc
	v_rsq_f32_e32 v102, v80
	v_pk_mul_f32 v[82:83], v[2:3], v[82:83]
	v_pk_mul_f32 v[80:81], v[0:1], v[100:101]
	global_store_dwordx4 v[104:105], v[80:83], off sc1
	s_add_u32 s22, s21, s2
	s_addc_u32 s23, s23, s3
	v_mul_f32_e32 v80, 0x45800000, v102
	v_cndmask_b32_e32 v100, v102, v80, vcc
	ds_read_b128 v[80:83], v112 offset:1040
	s_waitcnt lgkmcnt(1)
	v_pk_mul_f32 v[76:77], v[76:77], v[100:101] op_sel_hi:[1,0]
	v_pk_mul_f32 v[78:79], v[78:79], v[100:101] op_sel_hi:[1,0]
	v_pk_mul_f32 v[76:77], v[0:1], v[76:77]
	v_pk_mul_f32 v[78:79], v[2:3], v[78:79]
	v_lshl_add_u64 v[100:101], s[22:23], 0, v[108:109]
	global_store_dwordx4 v[100:101], v[76:79], off sc1
	s_add_i32 s22, s1, s20
	s_ashr_i32 s23, s22, 31
	s_waitcnt vmcnt(7)
	v_mov_b32_e32 v76, v85
	v_mov_b32_e32 v77, v86
	v_mov_b32_e32 v85, v87
	s_waitcnt vmcnt(6)
	v_mov_b32_e32 v78, v89
	v_mov_b32_e32 v79, v90
	v_mov_b32_e32 v89, v91
	v_pk_add_f32 v[76:77], v[76:77], v[84:85]
	v_pk_add_f32 v[78:79], v[78:79], v[88:89]
	v_mov_b32_e32 v85, v76
	v_mov_b32_e32 v84, v78
	v_mov_b32_e32 v76, v79
	v_pk_add_f32 v[76:77], v[84:85], v[76:77]
	s_lshl_b64 s[22:23], s[22:23], 12
	v_pk_fma_f32 v[84:85], v[76:77], s[6:7], v[110:111] op_sel_hi:[1,0,0]
	s_add_u32 s21, s10, s22
	v_mul_f32_e32 v76, 0x4b800000, v85
	v_cmp_gt_f32_e32 vcc, s7, v85
	s_addc_u32 s23, s11, s23
	s_add_u32 s22, s21, s2
	v_cndmask_b32_e32 v76, v85, v76, vcc
	v_rsq_f32_e32 v85, v76
	s_addc_u32 s23, s23, s3
	v_lshl_add_u64 v[86:87], s[22:23], 0, v[108:109]
	s_add_i32 s22, s14, s20
	v_mul_f32_e32 v88, 0x45800000, v85
	v_cndmask_b32_e32 v88, v85, v88, vcc
	v_mul_f32_e32 v85, 0x4b800000, v84
	v_cmp_gt_f32_e32 vcc, s7, v84
	ds_read_b128 v[76:79], v112 offset:2080
	s_ashr_i32 s23, s22, 31
	v_cndmask_b32_e32 v84, v84, v85, vcc
	v_rsq_f32_e32 v84, v84
	s_waitcnt lgkmcnt(1)
	v_pk_mul_f32 v[80:81], v[80:81], v[88:89] op_sel_hi:[1,0]
	v_pk_mul_f32 v[82:83], v[82:83], v[88:89] op_sel_hi:[1,0]
	s_lshl_b64 s[22:23], s[22:23], 12
	v_pk_mul_f32 v[82:83], v[2:3], v[82:83]
	v_pk_mul_f32 v[80:81], v[0:1], v[80:81]
	s_add_u32 s21, s10, s22
	global_store_dwordx4 v[86:87], v[80:83], off sc1
	s_addc_u32 s23, s11, s23
	s_add_u32 s22, s21, s2
	v_mul_f32_e32 v80, 0x45800000, v84
	v_cndmask_b32_e32 v84, v84, v80, vcc
	ds_read_b128 v[80:83], v112 offset:3120
	s_waitcnt lgkmcnt(1)
	v_pk_mul_f32 v[76:77], v[76:77], v[84:85] op_sel_hi:[1,0]
	v_pk_mul_f32 v[78:79], v[78:79], v[84:85] op_sel_hi:[1,0]
	s_addc_u32 s23, s23, s3
	v_pk_mul_f32 v[78:79], v[2:3], v[78:79]
	v_pk_mul_f32 v[76:77], v[0:1], v[76:77]
	v_lshl_add_u64 v[84:85], s[22:23], 0, v[108:109]
	global_store_dwordx4 v[84:85], v[76:79], off sc1
	s_add_i32 s22, s15, s20
	s_ashr_i32 s23, s22, 31
	s_waitcnt vmcnt(4)
	v_mov_b32_e32 v76, v97
	v_mov_b32_e32 v77, v98
	v_mov_b32_e32 v97, v99
	v_mov_b32_e32 v78, v93
	v_mov_b32_e32 v79, v94
	v_mov_b32_e32 v93, v95
	v_pk_add_f32 v[76:77], v[76:77], v[96:97]
	v_pk_add_f32 v[78:79], v[78:79], v[92:93]
	v_mov_b32_e32 v85, v76
	v_mov_b32_e32 v84, v78
	v_mov_b32_e32 v76, v79
	v_pk_add_f32 v[76:77], v[84:85], v[76:77]
	s_lshl_b64 s[22:23], s[22:23], 12
	v_pk_fma_f32 v[84:85], v[76:77], s[6:7], v[110:111] op_sel_hi:[1,0,0]
	s_add_u32 s21, s10, s22
	v_mul_f32_e32 v76, 0x4b800000, v85
	v_cmp_gt_f32_e32 vcc, s7, v85
	s_addc_u32 s23, s11, s23
	s_add_u32 s22, s21, s2
	v_cndmask_b32_e32 v76, v85, v76, vcc
	v_rsq_f32_e32 v85, v76
	s_addc_u32 s23, s23, s3
	v_lshl_add_u64 v[86:87], s[22:23], 0, v[108:109]
	s_add_i32 s22, s17, s20
	v_mul_f32_e32 v88, 0x45800000, v85
	v_cndmask_b32_e32 v88, v85, v88, vcc
	v_mul_f32_e32 v85, 0x4b800000, v84
	v_cmp_gt_f32_e32 vcc, s7, v84
	ds_read_b128 v[76:79], v112 offset:4160
	s_ashr_i32 s23, s22, 31
	v_cndmask_b32_e32 v84, v84, v85, vcc
	v_rsq_f32_e32 v84, v84
	s_waitcnt lgkmcnt(1)
	v_pk_mul_f32 v[80:81], v[88:89], v[80:81] op_sel_hi:[0,1]
	v_pk_mul_f32 v[82:83], v[88:89], v[82:83] op_sel_hi:[0,1]
	s_lshl_b64 s[22:23], s[22:23], 12
	v_pk_mul_f32 v[82:83], v[2:3], v[82:83]
	v_pk_mul_f32 v[80:81], v[0:1], v[80:81]
	s_add_u32 s21, s10, s22
	global_store_dwordx4 v[86:87], v[80:83], off sc1
	s_addc_u32 s23, s11, s23
	s_add_u32 s22, s21, s2
	v_mul_f32_e32 v80, 0x45800000, v84
	v_cndmask_b32_e32 v84, v84, v80, vcc
	ds_read_b128 v[80:83], v112 offset:5200
	s_waitcnt lgkmcnt(1)
	v_pk_mul_f32 v[76:77], v[84:85], v[76:77] op_sel_hi:[0,1]
	v_pk_mul_f32 v[78:79], v[84:85], v[78:79] op_sel_hi:[0,1]
	s_addc_u32 s23, s23, s3
	v_pk_mul_f32 v[78:79], v[2:3], v[78:79]
	v_pk_mul_f32 v[76:77], v[0:1], v[76:77]
	v_lshl_add_u64 v[84:85], s[22:23], 0, v[108:109]
	global_store_dwordx4 v[84:85], v[76:79], off sc1
	s_add_i32 s22, s18, s20
	s_ashr_i32 s23, s22, 31
	v_mov_b32_e32 v76, v73
	v_mov_b32_e32 v77, v74
	v_mov_b32_e32 v73, v75
	v_mov_b32_e32 v74, v37
	v_mov_b32_e32 v75, v38
	v_mov_b32_e32 v37, v39
	v_pk_add_f32 v[72:73], v[76:77], v[72:73]
	v_pk_add_f32 v[36:37], v[74:75], v[36:37]
	v_mov_b32_e32 v39, v72
	v_mov_b32_e32 v38, v36
	v_mov_b32_e32 v72, v37
	v_pk_add_f32 v[36:37], v[38:39], v[72:73]
	s_lshl_b64 s[22:23], s[22:23], 12
	v_pk_fma_f32 v[72:73], v[36:37], s[6:7], v[110:111] op_sel_hi:[1,0,0]
	s_add_u32 s21, s10, s22
	v_mul_f32_e32 v36, 0x4b800000, v73
	v_cmp_gt_f32_e32 vcc, s7, v73
	s_addc_u32 s23, s11, s23
	s_add_u32 s22, s21, s2
	v_cndmask_b32_e32 v36, v73, v36, vcc
	v_rsq_f32_e32 v73, v36
	s_addc_u32 s23, s23, s3
	s_add_i32 s20, s19, s20
	s_ashr_i32 s21, s20, 31
	v_mul_f32_e32 v74, 0x45800000, v73
	v_cndmask_b32_e32 v74, v73, v74, vcc
	v_mul_f32_e32 v73, 0x4b800000, v72
	v_cmp_gt_f32_e32 vcc, s7, v72
	s_waitcnt lgkmcnt(0)
	v_pk_mul_f32 v[78:79], v[74:75], v[80:81] op_sel_hi:[0,1]
	ds_read_b128 v[36:39], v112 offset:6240
	v_cndmask_b32_e32 v72, v72, v73, vcc
	v_rsq_f32_e32 v80, v72
	s_lshl_b64 s[20:21], s[20:21], 12
	v_pk_mul_f32 v[74:75], v[74:75], v[82:83] op_sel_hi:[0,1]
	s_add_u32 s20, s10, s20
	v_lshl_add_u64 v[76:77], s[22:23], 0, v[108:109]
	v_pk_mul_f32 v[74:75], v[2:3], v[74:75]
	v_pk_mul_f32 v[72:73], v[0:1], v[78:79]
	s_addc_u32 s21, s11, s21
	global_store_dwordx4 v[76:77], v[72:75], off sc1
	s_add_u32 s20, s20, s2
	s_addc_u32 s21, s21, s3
	v_mul_f32_e32 v72, 0x45800000, v80
	v_cndmask_b32_e32 v72, v80, v72, vcc
	s_waitcnt lgkmcnt(0)
	v_pk_mul_f32 v[36:37], v[72:73], v[36:37] op_sel_hi:[0,1]
	v_pk_mul_f32 v[38:39], v[72:73], v[38:39] op_sel_hi:[0,1]
	v_lshl_add_u64 v[72:73], s[20:21], 0, v[108:109]
	s_add_i32 s20, s9, 0x80
	s_add_i32 s21, s16, s20
	s_or_b32 s22, s21, s8
	s_ashr_i32 s23, s22, 31
	s_lshl_b64 s[22:23], s[22:23], 4
	s_add_u32 s22, s4, s22
	v_pk_mul_f32 v[38:39], v[2:3], v[38:39]
	v_pk_mul_f32 v[36:37], v[0:1], v[36:37]
	s_addc_u32 s23, s5, s23
	global_store_dwordx4 v[72:73], v[36:39], off sc1
	s_barrier
	ds_write_b128 v136, v[64:67]
	ds_write_b128 v136, v[60:63] offset:16
	ds_write_b128 v136, v[56:59] offset:512
	ds_write_b128 v136, v[48:51] offset:528
	ds_write_b128 v136, v[52:55] offset:16640
	ds_write_b128 v136, v[44:47] offset:16656
	ds_write_b128 v136, v[40:43] offset:17152
	ds_write_b128 v136, v[68:71] offset:17168
	s_waitcnt lgkmcnt(0)
	s_barrier
	global_load_dwordx4 v[44:47], v113, s[22:23]
	global_load_dwordx4 v[48:51], v113, s[22:23] offset:16
	global_load_dwordx4 v[52:55], v113, s[22:23] offset:32
	global_load_dwordx4 v[56:59], v113, s[22:23] offset:48
	s_or_b32 s22, s21, s13
	s_ashr_i32 s23, s22, 31
	s_lshl_b64 s[22:23], s[22:23], 4
	s_add_u32 s22, s4, s22
	s_addc_u32 s23, s5, s23
	global_load_dwordx4 v[36:39], v113, s[22:23] offset:48
	global_load_dwordx4 v[40:43], v113, s[22:23] offset:32
	global_load_dwordx4 v[60:63], v113, s[22:23] offset:16
	global_load_dwordx4 v[64:67], v113, s[22:23]
	s_add_i32 s22, s12, s20
	s_ashr_i32 s23, s22, 31
	ds_read_b128 v[68:71], v114
	s_lshl_b64 s[22:23], s[22:23], 12
	s_add_u32 s21, s10, s22
	s_addc_u32 s23, s11, s23
	s_add_u32 s22, s21, s2
	s_addc_u32 s23, s23, s3
	s_waitcnt vmcnt(7)
	v_mov_b32_e32 v72, v45
	v_mov_b32_e32 v73, v46
	v_mov_b32_e32 v45, v47
	s_waitcnt vmcnt(6)
	v_mov_b32_e32 v46, v49
	v_mov_b32_e32 v47, v50
	v_mov_b32_e32 v49, v51
	v_pk_add_f32 v[44:45], v[72:73], v[44:45]
	v_pk_add_f32 v[46:47], v[46:47], v[48:49]
	v_mov_b32_e32 v49, v44
	v_mov_b32_e32 v48, v46
	v_mov_b32_e32 v44, v47
	v_pk_add_f32 v[44:45], v[48:49], v[44:45]
	v_lshl_add_u64 v[72:73], s[22:23], 0, v[108:109]
	v_pk_fma_f32 v[48:49], v[44:45], s[6:7], v[110:111] op_sel_hi:[1,0,0]
	s_add_i32 s22, s0, s20
	v_mul_f32_e32 v44, 0x4b800000, v49
	v_cmp_gt_f32_e32 vcc, s7, v49
	s_ashr_i32 s23, s22, 31
	s_lshl_b64 s[22:23], s[22:23], 12
	v_cndmask_b32_e32 v44, v49, v44, vcc
	v_rsq_f32_e32 v49, v44
	ds_read_b128 v[44:47], v112
	s_add_u32 s21, s10, s22
	s_addc_u32 s23, s11, s23
	v_mul_f32_e32 v50, 0x45800000, v49
	v_cndmask_b32_e32 v50, v49, v50, vcc
	v_mul_f32_e32 v49, 0x4b800000, v48
	v_cmp_gt_f32_e32 vcc, s7, v48
	s_waitcnt lgkmcnt(1)
	v_pk_mul_f32 v[68:69], v[68:69], v[50:51] op_sel_hi:[1,0]
	v_pk_mul_f32 v[50:51], v[70:71], v[50:51] op_sel_hi:[1,0]
	v_cndmask_b32_e32 v48, v48, v49, vcc
	v_rsq_f32_e32 v70, v48
	v_pk_mul_f32 v[50:51], v[2:3], v[50:51]
	v_pk_mul_f32 v[48:49], v[0:1], v[68:69]
	global_store_dwordx4 v[72:73], v[48:51], off sc1
	s_add_u32 s22, s21, s2
	s_addc_u32 s23, s23, s3
	v_mul_f32_e32 v48, 0x45800000, v70
	v_cndmask_b32_e32 v68, v70, v48, vcc
	ds_read_b128 v[48:51], v112 offset:1040
	s_waitcnt lgkmcnt(1)
	v_pk_mul_f32 v[44:45], v[44:45], v[68:69] op_sel_hi:[1,0]
	v_pk_mul_f32 v[46:47], v[46:47], v[68:69] op_sel_hi:[1,0]
	v_pk_mul_f32 v[44:45], v[0:1], v[44:45]
	v_pk_mul_f32 v[46:47], v[2:3], v[46:47]
	v_lshl_add_u64 v[68:69], s[22:23], 0, v[108:109]
	global_store_dwordx4 v[68:69], v[44:47], off sc1
	s_add_i32 s22, s1, s20
	s_ashr_i32 s23, s22, 31
	s_waitcnt vmcnt(7)
	v_mov_b32_e32 v44, v53
	v_mov_b32_e32 v45, v54
	v_mov_b32_e32 v53, v55
	s_waitcnt vmcnt(6)
	v_mov_b32_e32 v46, v57
	v_mov_b32_e32 v47, v58
	v_mov_b32_e32 v57, v59
	v_pk_add_f32 v[44:45], v[44:45], v[52:53]
	v_pk_add_f32 v[46:47], v[46:47], v[56:57]
	v_mov_b32_e32 v53, v44
	v_mov_b32_e32 v52, v46
	v_mov_b32_e32 v44, v47
	v_pk_add_f32 v[44:45], v[52:53], v[44:45]
	s_lshl_b64 s[22:23], s[22:23], 12
	v_pk_fma_f32 v[52:53], v[44:45], s[6:7], v[110:111] op_sel_hi:[1,0,0]
	s_add_u32 s21, s10, s22
	v_mul_f32_e32 v44, 0x4b800000, v53
	v_cmp_gt_f32_e32 vcc, s7, v53
	s_addc_u32 s23, s11, s23
	s_add_u32 s22, s21, s2
	v_cndmask_b32_e32 v44, v53, v44, vcc
	v_rsq_f32_e32 v53, v44
	s_addc_u32 s23, s23, s3
	v_lshl_add_u64 v[54:55], s[22:23], 0, v[108:109]
	s_add_i32 s22, s14, s20
	v_mul_f32_e32 v56, 0x45800000, v53
	v_cndmask_b32_e32 v56, v53, v56, vcc
	v_mul_f32_e32 v53, 0x4b800000, v52
	v_cmp_gt_f32_e32 vcc, s7, v52
	ds_read_b128 v[44:47], v112 offset:2080
	s_ashr_i32 s23, s22, 31
	v_cndmask_b32_e32 v52, v52, v53, vcc
	v_rsq_f32_e32 v52, v52
	s_waitcnt lgkmcnt(1)
	v_pk_mul_f32 v[48:49], v[48:49], v[56:57] op_sel_hi:[1,0]
	v_pk_mul_f32 v[50:51], v[50:51], v[56:57] op_sel_hi:[1,0]
	s_lshl_b64 s[22:23], s[22:23], 12
	v_pk_mul_f32 v[50:51], v[2:3], v[50:51]
	v_pk_mul_f32 v[48:49], v[0:1], v[48:49]
	s_add_u32 s21, s10, s22
	global_store_dwordx4 v[54:55], v[48:51], off sc1
	s_addc_u32 s23, s11, s23
	s_add_u32 s22, s21, s2
	v_mul_f32_e32 v48, 0x45800000, v52
	v_cndmask_b32_e32 v52, v52, v48, vcc
	ds_read_b128 v[48:51], v112 offset:3120
	s_waitcnt lgkmcnt(1)
	v_pk_mul_f32 v[44:45], v[44:45], v[52:53] op_sel_hi:[1,0]
	v_pk_mul_f32 v[46:47], v[46:47], v[52:53] op_sel_hi:[1,0]
	s_addc_u32 s23, s23, s3
	v_pk_mul_f32 v[46:47], v[2:3], v[46:47]
	v_pk_mul_f32 v[44:45], v[0:1], v[44:45]
	v_lshl_add_u64 v[52:53], s[22:23], 0, v[108:109]
	global_store_dwordx4 v[52:53], v[44:47], off sc1
	s_add_i32 s22, s15, s20
	s_ashr_i32 s23, s22, 31
	s_waitcnt vmcnt(4)
	v_mov_b32_e32 v44, v65
	v_mov_b32_e32 v45, v66
	v_mov_b32_e32 v65, v67
	v_mov_b32_e32 v46, v61
	v_mov_b32_e32 v47, v62
	v_mov_b32_e32 v61, v63
	v_pk_add_f32 v[44:45], v[44:45], v[64:65]
	v_pk_add_f32 v[46:47], v[46:47], v[60:61]
	v_mov_b32_e32 v53, v44
	v_mov_b32_e32 v52, v46
	v_mov_b32_e32 v44, v47
	v_pk_add_f32 v[44:45], v[52:53], v[44:45]
	s_lshl_b64 s[22:23], s[22:23], 12
	v_pk_fma_f32 v[52:53], v[44:45], s[6:7], v[110:111] op_sel_hi:[1,0,0]
	s_add_u32 s21, s10, s22
	v_mul_f32_e32 v44, 0x4b800000, v53
	v_cmp_gt_f32_e32 vcc, s7, v53
	s_addc_u32 s23, s11, s23
	s_add_u32 s22, s21, s2
	v_cndmask_b32_e32 v44, v53, v44, vcc
	v_rsq_f32_e32 v53, v44
	s_addc_u32 s23, s23, s3
	v_lshl_add_u64 v[54:55], s[22:23], 0, v[108:109]
	s_add_i32 s22, s17, s20
	v_mul_f32_e32 v56, 0x45800000, v53
	v_cndmask_b32_e32 v56, v53, v56, vcc
	v_mul_f32_e32 v53, 0x4b800000, v52
	v_cmp_gt_f32_e32 vcc, s7, v52
	ds_read_b128 v[44:47], v112 offset:4160
	s_ashr_i32 s23, s22, 31
	v_cndmask_b32_e32 v52, v52, v53, vcc
	v_rsq_f32_e32 v52, v52
	s_waitcnt lgkmcnt(1)
	v_pk_mul_f32 v[48:49], v[56:57], v[48:49] op_sel_hi:[0,1]
	v_pk_mul_f32 v[50:51], v[56:57], v[50:51] op_sel_hi:[0,1]
	s_lshl_b64 s[22:23], s[22:23], 12
	v_pk_mul_f32 v[50:51], v[2:3], v[50:51]
	v_pk_mul_f32 v[48:49], v[0:1], v[48:49]
	s_add_u32 s21, s10, s22
	global_store_dwordx4 v[54:55], v[48:51], off sc1
	s_addc_u32 s23, s11, s23
	s_add_u32 s22, s21, s2
	v_mul_f32_e32 v48, 0x45800000, v52
	v_cndmask_b32_e32 v52, v52, v48, vcc
	ds_read_b128 v[48:51], v112 offset:5200
	s_waitcnt lgkmcnt(1)
	v_pk_mul_f32 v[44:45], v[52:53], v[44:45] op_sel_hi:[0,1]
	v_pk_mul_f32 v[46:47], v[52:53], v[46:47] op_sel_hi:[0,1]
	s_addc_u32 s23, s23, s3
	v_pk_mul_f32 v[46:47], v[2:3], v[46:47]
	v_pk_mul_f32 v[44:45], v[0:1], v[44:45]
	v_lshl_add_u64 v[52:53], s[22:23], 0, v[108:109]
	global_store_dwordx4 v[52:53], v[44:47], off sc1
	s_add_i32 s22, s18, s20
	s_ashr_i32 s23, s22, 31
	v_mov_b32_e32 v44, v41
	v_mov_b32_e32 v45, v42
	v_mov_b32_e32 v41, v43
	v_mov_b32_e32 v42, v37
	v_mov_b32_e32 v43, v38
	v_mov_b32_e32 v37, v39
	v_pk_add_f32 v[40:41], v[44:45], v[40:41]
	v_pk_add_f32 v[36:37], v[42:43], v[36:37]
	v_mov_b32_e32 v39, v40
	v_mov_b32_e32 v38, v36
	v_mov_b32_e32 v40, v37
	v_pk_add_f32 v[36:37], v[38:39], v[40:41]
	s_lshl_b64 s[22:23], s[22:23], 12
	v_pk_fma_f32 v[40:41], v[36:37], s[6:7], v[110:111] op_sel_hi:[1,0,0]
	s_add_u32 s21, s10, s22
	v_mul_f32_e32 v36, 0x4b800000, v41
	v_cmp_gt_f32_e32 vcc, s7, v41
	s_addc_u32 s23, s11, s23
	s_add_u32 s22, s21, s2
	v_cndmask_b32_e32 v36, v41, v36, vcc
	v_rsq_f32_e32 v41, v36
	s_addc_u32 s23, s23, s3
	s_add_i32 s20, s19, s20
	s_ashr_i32 s21, s20, 31
	v_mul_f32_e32 v42, 0x45800000, v41
	v_cndmask_b32_e32 v42, v41, v42, vcc
	v_mul_f32_e32 v41, 0x4b800000, v40
	v_cmp_gt_f32_e32 vcc, s7, v40
	s_waitcnt lgkmcnt(0)
	v_pk_mul_f32 v[46:47], v[42:43], v[48:49] op_sel_hi:[0,1]
	s_lshl_b64 s[20:21], s[20:21], 12
	v_cndmask_b32_e32 v40, v40, v41, vcc
	v_rsq_f32_e32 v48, v40
	ds_read_b128 v[36:39], v112 offset:6240
	s_add_u32 s20, s10, s20
	v_pk_mul_f32 v[42:43], v[42:43], v[50:51] op_sel_hi:[0,1]
	s_addc_u32 s21, s11, s21
	v_lshl_add_u64 v[44:45], s[22:23], 0, v[108:109]
	v_pk_mul_f32 v[42:43], v[2:3], v[42:43]
	v_pk_mul_f32 v[40:41], v[0:1], v[46:47]
	s_add_u32 s20, s20, s2
	global_store_dwordx4 v[44:45], v[40:43], off sc1
	s_addc_u32 s21, s21, s3
	s_addk_i32 s9, 0xa0
	v_mul_f32_e32 v40, 0x45800000, v48
	v_cndmask_b32_e32 v40, v48, v40, vcc
	s_add_i32 s16, s16, s9
	s_waitcnt lgkmcnt(0)
	v_pk_mul_f32 v[36:37], v[40:41], v[36:37] op_sel_hi:[0,1]
	v_pk_mul_f32 v[38:39], v[40:41], v[38:39] op_sel_hi:[0,1]
	v_lshl_add_u64 v[40:41], s[20:21], 0, v[108:109]
	s_or_b32 s20, s16, s8
	s_ashr_i32 s21, s20, 31
	s_lshl_b64 s[20:21], s[20:21], 4
	s_add_u32 s20, s4, s20
	v_pk_mul_f32 v[38:39], v[2:3], v[38:39]
	v_pk_mul_f32 v[36:37], v[0:1], v[36:37]
	s_addc_u32 s21, s5, s21
	global_store_dwordx4 v[40:41], v[36:39], off sc1
	s_barrier
	ds_write_b128 v136, v[32:35]
	ds_write_b128 v136, v[28:31] offset:16
	ds_write_b128 v136, v[24:27] offset:512
	ds_write_b128 v136, v[16:19] offset:528
	ds_write_b128 v136, v[20:23] offset:16640
	ds_write_b128 v136, v[12:15] offset:16656
	ds_write_b128 v136, v[8:11] offset:17152
	ds_write_b128 v136, v[4:7] offset:17168
	s_waitcnt lgkmcnt(0)
	s_barrier
	global_load_dwordx4 v[12:15], v113, s[20:21]
	global_load_dwordx4 v[16:19], v113, s[20:21] offset:16
	global_load_dwordx4 v[20:23], v113, s[20:21] offset:32
	global_load_dwordx4 v[24:27], v113, s[20:21] offset:48
	s_or_b32 s20, s16, s13
	s_ashr_i32 s21, s20, 31
	s_lshl_b64 s[20:21], s[20:21], 4
	s_add_u32 s4, s4, s20
	s_addc_u32 s5, s5, s21
	global_load_dwordx4 v[4:7], v113, s[4:5] offset:48
	global_load_dwordx4 v[8:11], v113, s[4:5] offset:32
	global_load_dwordx4 v[28:31], v113, s[4:5] offset:16
	global_load_dwordx4 v[32:35], v113, s[4:5]
	s_add_i32 s4, s12, s9
	s_ashr_i32 s5, s4, 31
	ds_read_b128 v[36:39], v114
	s_lshl_b64 s[4:5], s[4:5], 12
	s_add_u32 s4, s10, s4
	s_addc_u32 s5, s11, s5
	s_add_u32 s4, s4, s2
	s_addc_u32 s5, s5, s3
	s_waitcnt vmcnt(7)
	v_mov_b32_e32 v40, v13
	v_mov_b32_e32 v41, v14
	v_mov_b32_e32 v13, v15
	s_waitcnt vmcnt(6)
	v_mov_b32_e32 v14, v17
	v_mov_b32_e32 v15, v18
	v_mov_b32_e32 v17, v19
	v_pk_add_f32 v[12:13], v[40:41], v[12:13]
	v_pk_add_f32 v[14:15], v[14:15], v[16:17]
	v_mov_b32_e32 v17, v12
	v_mov_b32_e32 v16, v14
	v_mov_b32_e32 v12, v15
	v_pk_add_f32 v[12:13], v[16:17], v[12:13]
	v_lshl_add_u64 v[40:41], s[4:5], 0, v[108:109]
	v_pk_fma_f32 v[16:17], v[12:13], s[6:7], v[110:111] op_sel_hi:[1,0,0]
	s_add_i32 s4, s0, s9
	v_mul_f32_e32 v12, 0x4b800000, v17
	v_cmp_gt_f32_e32 vcc, s7, v17
	s_ashr_i32 s5, s4, 31
	s_lshl_b64 s[4:5], s[4:5], 12
	v_cndmask_b32_e32 v12, v17, v12, vcc
	v_rsq_f32_e32 v17, v12
	ds_read_b128 v[12:15], v112
	s_add_u32 s0, s10, s4
	s_addc_u32 s5, s11, s5
	v_mul_f32_e32 v18, 0x45800000, v17
	v_cndmask_b32_e32 v18, v17, v18, vcc
	v_mul_f32_e32 v17, 0x4b800000, v16
	v_cmp_gt_f32_e32 vcc, s7, v16
	s_waitcnt lgkmcnt(1)
	v_pk_mul_f32 v[36:37], v[36:37], v[18:19] op_sel_hi:[1,0]
	v_pk_mul_f32 v[18:19], v[38:39], v[18:19] op_sel_hi:[1,0]
	v_cndmask_b32_e32 v16, v16, v17, vcc
	v_rsq_f32_e32 v38, v16
	v_pk_mul_f32 v[18:19], v[2:3], v[18:19]
	v_pk_mul_f32 v[16:17], v[0:1], v[36:37]
	global_store_dwordx4 v[40:41], v[16:19], off sc1
	s_add_u32 s4, s0, s2
	s_addc_u32 s5, s5, s3
	v_mul_f32_e32 v16, 0x45800000, v38
	v_cndmask_b32_e32 v36, v38, v16, vcc
	ds_read_b128 v[16:19], v112 offset:1040
	s_waitcnt lgkmcnt(1)
	v_pk_mul_f32 v[12:13], v[12:13], v[36:37] op_sel_hi:[1,0]
	v_pk_mul_f32 v[14:15], v[14:15], v[36:37] op_sel_hi:[1,0]
	v_pk_mul_f32 v[12:13], v[0:1], v[12:13]
	v_pk_mul_f32 v[14:15], v[2:3], v[14:15]
	v_lshl_add_u64 v[36:37], s[4:5], 0, v[108:109]
	global_store_dwordx4 v[36:37], v[12:15], off sc1
	s_add_i32 s0, s1, s9
	s_ashr_i32 s1, s0, 31
	s_waitcnt vmcnt(7)
	v_mov_b32_e32 v12, v21
	v_mov_b32_e32 v13, v22
	v_mov_b32_e32 v21, v23
	s_waitcnt vmcnt(6)
	v_mov_b32_e32 v14, v25
	v_mov_b32_e32 v15, v26
	v_mov_b32_e32 v25, v27
	v_pk_add_f32 v[12:13], v[12:13], v[20:21]
	v_pk_add_f32 v[14:15], v[14:15], v[24:25]
	v_mov_b32_e32 v21, v12
	v_mov_b32_e32 v20, v14
	v_mov_b32_e32 v12, v15
	v_pk_add_f32 v[12:13], v[20:21], v[12:13]
	s_lshl_b64 s[0:1], s[0:1], 12
	v_pk_fma_f32 v[20:21], v[12:13], s[6:7], v[110:111] op_sel_hi:[1,0,0]
	s_add_u32 s0, s10, s0
	v_mul_f32_e32 v12, 0x4b800000, v21
	v_cmp_gt_f32_e32 vcc, s7, v21
	s_addc_u32 s1, s11, s1
	s_add_u32 s0, s0, s2
	v_cndmask_b32_e32 v12, v21, v12, vcc
	v_rsq_f32_e32 v21, v12
	s_addc_u32 s1, s1, s3
	v_lshl_add_u64 v[22:23], s[0:1], 0, v[108:109]
	s_add_i32 s0, s14, s9
	v_mul_f32_e32 v24, 0x45800000, v21
	v_cndmask_b32_e32 v24, v21, v24, vcc
	v_mul_f32_e32 v21, 0x4b800000, v20
	v_cmp_gt_f32_e32 vcc, s7, v20
	ds_read_b128 v[12:15], v112 offset:2080
	s_ashr_i32 s1, s0, 31
	v_cndmask_b32_e32 v20, v20, v21, vcc
	v_rsq_f32_e32 v20, v20
	s_waitcnt lgkmcnt(1)
	v_pk_mul_f32 v[16:17], v[16:17], v[24:25] op_sel_hi:[1,0]
	v_pk_mul_f32 v[18:19], v[18:19], v[24:25] op_sel_hi:[1,0]
	s_lshl_b64 s[0:1], s[0:1], 12
	v_pk_mul_f32 v[18:19], v[2:3], v[18:19]
	v_pk_mul_f32 v[16:17], v[0:1], v[16:17]
	s_add_u32 s0, s10, s0
	global_store_dwordx4 v[22:23], v[16:19], off sc1
	s_addc_u32 s1, s11, s1
	s_add_u32 s0, s0, s2
	v_mul_f32_e32 v16, 0x45800000, v20
	v_cndmask_b32_e32 v20, v20, v16, vcc
	ds_read_b128 v[16:19], v112 offset:3120
	s_waitcnt lgkmcnt(1)
	v_pk_mul_f32 v[12:13], v[12:13], v[20:21] op_sel_hi:[1,0]
	v_pk_mul_f32 v[14:15], v[14:15], v[20:21] op_sel_hi:[1,0]
	s_addc_u32 s1, s1, s3
	v_pk_mul_f32 v[14:15], v[2:3], v[14:15]
	v_pk_mul_f32 v[12:13], v[0:1], v[12:13]
	v_lshl_add_u64 v[20:21], s[0:1], 0, v[108:109]
	global_store_dwordx4 v[20:21], v[12:15], off sc1
	s_add_i32 s0, s15, s9
	s_ashr_i32 s1, s0, 31
	s_waitcnt vmcnt(4)
	v_mov_b32_e32 v12, v33
	v_mov_b32_e32 v13, v34
	v_mov_b32_e32 v33, v35
	v_mov_b32_e32 v14, v29
	v_mov_b32_e32 v15, v30
	v_mov_b32_e32 v29, v31
	v_pk_add_f32 v[12:13], v[12:13], v[32:33]
	v_pk_add_f32 v[14:15], v[14:15], v[28:29]
	v_mov_b32_e32 v21, v12
	v_mov_b32_e32 v20, v14
	v_mov_b32_e32 v12, v15
	v_pk_add_f32 v[12:13], v[20:21], v[12:13]
	s_lshl_b64 s[0:1], s[0:1], 12
	v_pk_fma_f32 v[20:21], v[12:13], s[6:7], v[110:111] op_sel_hi:[1,0,0]
	s_add_u32 s0, s10, s0
	v_mul_f32_e32 v12, 0x4b800000, v21
	v_cmp_gt_f32_e32 vcc, s7, v21
	s_addc_u32 s1, s11, s1
	s_add_u32 s0, s0, s2
	v_cndmask_b32_e32 v12, v21, v12, vcc
	v_rsq_f32_e32 v21, v12
	s_addc_u32 s1, s1, s3
	v_lshl_add_u64 v[22:23], s[0:1], 0, v[108:109]
	s_add_i32 s0, s17, s9
	v_mul_f32_e32 v24, 0x45800000, v21
	v_cndmask_b32_e32 v24, v21, v24, vcc
	v_mul_f32_e32 v21, 0x4b800000, v20
	v_cmp_gt_f32_e32 vcc, s7, v20
	ds_read_b128 v[12:15], v112 offset:4160
	s_ashr_i32 s1, s0, 31
	v_cndmask_b32_e32 v20, v20, v21, vcc
	v_rsq_f32_e32 v20, v20
	s_waitcnt lgkmcnt(1)
	v_pk_mul_f32 v[16:17], v[24:25], v[16:17] op_sel_hi:[0,1]
	v_pk_mul_f32 v[18:19], v[24:25], v[18:19] op_sel_hi:[0,1]
	s_lshl_b64 s[0:1], s[0:1], 12
	v_pk_mul_f32 v[18:19], v[2:3], v[18:19]
	v_pk_mul_f32 v[16:17], v[0:1], v[16:17]
	s_add_u32 s0, s10, s0
	global_store_dwordx4 v[22:23], v[16:19], off sc1
	s_addc_u32 s1, s11, s1
	s_add_u32 s0, s0, s2
	v_mul_f32_e32 v16, 0x45800000, v20
	v_cndmask_b32_e32 v20, v20, v16, vcc
	ds_read_b128 v[16:19], v112 offset:5200
	s_waitcnt lgkmcnt(1)
	v_pk_mul_f32 v[12:13], v[20:21], v[12:13] op_sel_hi:[0,1]
	v_pk_mul_f32 v[14:15], v[20:21], v[14:15] op_sel_hi:[0,1]
	s_addc_u32 s1, s1, s3
	v_pk_mul_f32 v[14:15], v[2:3], v[14:15]
	v_pk_mul_f32 v[12:13], v[0:1], v[12:13]
	v_lshl_add_u64 v[20:21], s[0:1], 0, v[108:109]
	global_store_dwordx4 v[20:21], v[12:15], off sc1
	s_add_i32 s0, s18, s9
	s_ashr_i32 s1, s0, 31
	v_mov_b32_e32 v12, v9
	v_mov_b32_e32 v13, v10
	v_mov_b32_e32 v9, v11
	v_mov_b32_e32 v10, v5
	v_mov_b32_e32 v11, v6
	v_mov_b32_e32 v5, v7
	v_pk_add_f32 v[8:9], v[12:13], v[8:9]
	v_pk_add_f32 v[4:5], v[10:11], v[4:5]
	v_mov_b32_e32 v7, v8
	v_mov_b32_e32 v6, v4
	v_mov_b32_e32 v8, v5
	v_pk_add_f32 v[4:5], v[6:7], v[8:9]
	s_lshl_b64 s[0:1], s[0:1], 12
	v_pk_fma_f32 v[8:9], v[4:5], s[6:7], v[110:111] op_sel_hi:[1,0,0]
	s_add_u32 s0, s10, s0
	v_mul_f32_e32 v4, 0x4b800000, v9
	v_cmp_gt_f32_e32 vcc, s7, v9
	s_addc_u32 s1, s11, s1
	s_add_u32 s0, s0, s2
	v_cndmask_b32_e32 v4, v9, v4, vcc
	v_rsq_f32_e32 v9, v4
	s_addc_u32 s1, s1, s3
	v_lshl_add_u64 v[12:13], s[0:1], 0, v[108:109]
	s_add_i32 s0, s19, s9
	v_mul_f32_e32 v10, 0x45800000, v9
	v_cndmask_b32_e32 v10, v9, v10, vcc
	v_mul_f32_e32 v9, 0x4b800000, v8
	v_cmp_gt_f32_e32 vcc, s7, v8
	s_waitcnt lgkmcnt(0)
	v_pk_mul_f32 v[14:15], v[10:11], v[16:17] op_sel_hi:[0,1]
	ds_read_b128 v[4:7], v112 offset:6240
	v_cndmask_b32_e32 v8, v8, v9, vcc
	v_rsq_f32_e32 v16, v8
	s_ashr_i32 s1, s0, 31
	v_pk_mul_f32 v[10:11], v[10:11], v[18:19] op_sel_hi:[0,1]
	s_lshl_b64 s[0:1], s[0:1], 12
	v_pk_mul_f32 v[10:11], v[2:3], v[10:11]
	v_pk_mul_f32 v[8:9], v[0:1], v[14:15]
	s_add_u32 s0, s10, s0
	global_store_dwordx4 v[12:13], v[8:11], off sc1
	s_addc_u32 s1, s11, s1
	s_add_u32 s0, s0, s2
	v_mul_f32_e32 v8, 0x45800000, v16
	v_cndmask_b32_e32 v8, v16, v8, vcc
	s_waitcnt lgkmcnt(0)
	v_pk_mul_f32 v[4:5], v[8:9], v[4:5] op_sel_hi:[0,1]
	v_pk_mul_f32 v[6:7], v[8:9], v[6:7] op_sel_hi:[0,1]
	s_addc_u32 s1, s1, s3
	v_pk_mul_f32 v[2:3], v[2:3], v[6:7]
	v_pk_mul_f32 v[0:1], v[0:1], v[4:5]
	v_lshl_add_u64 v[4:5], s[0:1], 0, v[108:109]
	global_store_dwordx4 v[4:5], v[0:3], off sc1
	s_barrier
